# P1 unit header: drop vmcnt(0) on the back edge (only first entry needs it); sound wait before QKV cache-copy store for waves without stores
# speedup vs baseline: 1.0025x; 1.0025x over previous
.LBB0_359:
	s_and_b32 s36, s1, 3
	s_lshl_b32 s83, s2, 6
	s_lshl_b32 s1, s2, 13
	s_lshl_b32 s10, s36, 12
	v_readlane_b32 s12, v246, 2
	v_readlane_b32 s13, v246, 3
	s_add_u32 s38, s12, 0x7500000
	s_addc_u32 s39, s13, 0
	s_add_u32 s40, s12, 0x1be00000
	s_mov_b64 s[42:43], 0x80
	s_addc_u32 s41, s13, 0
	s_add_i32 m0, s31, 0x18000
	v_lshl_add_u64 v[8:9], v[8:9], 0, s[42:43]
	s_waitcnt vmcnt(2)
	s_barrier
	global_load_lds_dwordx4 v[8:9], off
	v_lshl_add_u64 v[4:5], v[4:5], 0, s[42:43]
	s_add_i32 m0, s31, 0x1a000
	s_add_i32 s84, s31, 0x8000
	s_add_i32 s85, s31, 0xa000
	global_load_lds_dwordx4 v[4:5], off
	v_lshl_add_u64 v[2:3], v[2:3], 0, s[42:43]
	s_mov_b32 m0, s84
	s_add_u32 s2, s8, 0x40080
	global_load_lds_dwordx4 v[2:3], off
	v_lshl_add_u64 v[2:3], v[6:7], 0, s[42:43]
	s_mov_b32 m0, s85
	s_addc_u32 s3, s9, 0
	global_load_lds_dwordx4 v[2:3], off
	s_add_i32 m0, s31, 0x1c000
	v_lshl_add_u64 v[2:3], s[2:3], 0, v[164:165]
	global_load_lds_dwordx4 v[2:3], off
	v_lshl_add_u64 v[2:3], s[2:3], 0, v[168:169]
	s_add_i32 m0, s31, 0x1e000
	v_and_b32_e32 v1, 15, v0
	global_load_lds_dwordx4 v[2:3], off
	v_bfe_u32 v2, v0, 4, 2
	v_lshlrev_b32_e32 v170, 4, v2
	v_lshlrev_b32_e32 v3, 2, v0
	v_lshlrev_b32_e32 v172, 3, v2
	v_lshl_or_b32 v2, v1, 6, v170
	v_and_b32_e32 v3, 32, v3
	v_bitop3_b32 v4, v2, s1, v3 bitop3:0xde
	v_lshlrev_b32_e32 v2, 6, v0
	s_movk_i32 s1, 0x3c0
	s_cmpk_lt_u32 s0, 0x100
	v_and_or_b32 v2, v2, s1, v170
	s_cselect_b64 s[46:47], -1, 0
	s_and_b32 s0, s0, 0xffffff00
	v_bitop3_b32 v173, s10, v2, v3 bitop3:0xf6
	s_lshl_b32 s86, s36, 6
	v_or_b32_e32 v2, s0, v178
	v_or_b32_e32 v192, s86, v2
	v_and_b32_e32 v2, 3, v0
	v_add_u32_e32 v174, 26, v2
	v_lshl_add_u64 v[2:3], s[12:13], 0, v[170:171]
	s_mov_b64 s[0:1], 0xf800000
	v_lshl_add_u64 v[176:177], v[2:3], 0, s[0:1]
	v_lshlrev_b32_e32 v2, 8, v0
	v_and_b32_e32 v2, 0x18000, v2
	v_lshlrev_b32_e32 v3, 11, v12
	s_or_b32 s87, s52, 0x190
	s_add_i32 s0, s63, 0xfffff380
	v_or3_b32 v2, v10, v2, v3
	s_add_u32 s48, s28, 0x15370000
	v_add_u32_e32 v180, v2, v11
	v_lshlrev_b32_e32 v2, 4, v13
	s_addc_u32 s49, s29, 0
	v_and_b32_e32 v2, 0x38000, v2
	s_waitcnt vmcnt(6)
	s_add_u32 s50, s28, 0x15280000
	v_or3_b32 v2, v10, v2, v3
	s_mov_b32 s45, 0
	v_lshl_or_b32 v175, s36, 5, v172
	s_addc_u32 s51, s29, 0
	v_add_u32_e32 v182, v2, v11
	s_add_i32 s89, 0, 0x10000
	s_add_i32 s90, 0, 0x14000
	v_mbcnt_lo_u32_b32 v2, -1, 0
	v_or_b32_e32 v179, 0xfffffb80, v175
	v_add_u32_e32 v193, 0x200, v192
	v_add_u32_e32 v194, 0x400, v192
	v_add_u32_e32 v195, 0x600, v192
	v_or_b32_e32 v196, -4, v0
	s_mov_b32 s37, s45
	v_writelane_b32 v246, s63, 19
	v_mov_b32_e32 v181, v171
	v_mov_b32_e32 v183, v171
	v_add_u32_e32 v197, s89, v173
	v_add_u32_e32 v198, s90, v173
	v_add_u32_e32 v199, 0, v4
	s_movk_i32 s76, 0x80
	s_movk_i32 s92, 0xfb10
	s_mov_b32 s88, 0x34a0000
	s_movk_i32 s94, 0x7fff
	s_mov_b32 s95, 0x8080
	s_movk_i32 s93, 0xfe1
	v_mov_b32_e32 v200, 0x358637bd
	v_mov_b32_e32 v201, 0xfffff01e
	v_mov_b32_e32 v202, 0x3e38aa3b
	v_mbcnt_hi_u32_b32 v203, -1, v2
	v_mov_b32_e32 v204, 0x3000000
	s_mov_b32 s1, s30
	s_mov_b32 s14, 0
	s_barrier
	v_writelane_b32 v246, s0, 20
	s_waitcnt vmcnt(0)
	s_branch .LBB0_362

.LBB0_367:
	s_ashr_i32 s55, s54, 31
	s_lshl_b64 s[2:3], s[54:55], 19
	s_add_u32 s58, s4, s2
	s_addc_u32 s59, s5, s3
	s_and_b64 s[2:3], s[56:57], exec
	s_cselect_b32 s2, s59, s7
	s_cselect_b32 s3, s58, s6
	s_ashr_i32 s53, s52, 31
	s_lshl_b64 s[10:11], s[52:53], 19
	s_add_u32 s60, s15, s10
	s_addc_u32 s61, s78, s11
	s_and_b64 s[10:11], s[56:57], exec
	s_cselect_b32 s12, s61, s9
	s_cselect_b32 s13, s60, s8
	s_add_u32 s6, s6, 0x40080
	s_addc_u32 s7, s7, 0
	s_add_u32 s24, s8, 0x100
	v_mov_b64_e32 v[2:3], 0
	s_addc_u32 s25, s9, 0
	s_mov_b32 s26, -2
	v_mov_b64_e32 v[4:5], 0
	v_mov_b64_e32 v[6:7], 0
	v_mov_b64_e32 v[8:9], 0
	v_mov_b64_e32 v[18:19], 0
	v_mov_b64_e32 v[20:21], 0
	v_mov_b64_e32 v[22:23], 0
	v_mov_b64_e32 v[24:25], 0
	v_mov_b64_e32 v[34:35], 0
	v_mov_b64_e32 v[36:37], 0
	v_mov_b64_e32 v[38:39], 0
	v_mov_b64_e32 v[40:41], 0
	v_mov_b64_e32 v[50:51], 0
	v_mov_b64_e32 v[52:53], 0
	v_mov_b64_e32 v[54:55], 0
	v_mov_b64_e32 v[56:57], 0
	v_mov_b64_e32 v[10:11], 0
	v_mov_b64_e32 v[12:13], 0
	v_mov_b64_e32 v[14:15], 0
	v_mov_b64_e32 v[16:17], 0
	v_mov_b64_e32 v[26:27], 0
	v_mov_b64_e32 v[28:29], 0
	v_mov_b64_e32 v[30:31], 0
	v_mov_b64_e32 v[32:33], 0
	v_mov_b64_e32 v[42:43], 0
	v_mov_b64_e32 v[44:45], 0
	v_mov_b64_e32 v[46:47], 0
	v_mov_b64_e32 v[48:49], 0
	v_mov_b64_e32 v[58:59], 0
	v_mov_b64_e32 v[60:61], 0
	v_mov_b64_e32 v[62:63], 0
	v_mov_b64_e32 v[64:65], 0
	v_mov_b64_e32 v[66:67], 0
	v_mov_b64_e32 v[68:69], 0
	v_mov_b64_e32 v[70:71], 0
	v_mov_b64_e32 v[72:73], 0
	v_mov_b64_e32 v[82:83], 0
	v_mov_b64_e32 v[84:85], 0
	v_mov_b64_e32 v[86:87], 0
	v_mov_b64_e32 v[88:89], 0
	v_mov_b64_e32 v[98:99], 0
	v_mov_b64_e32 v[100:101], 0
	v_mov_b64_e32 v[102:103], 0
	v_mov_b64_e32 v[104:105], 0
	v_mov_b64_e32 v[118:119], 0
	v_mov_b64_e32 v[120:121], 0
	v_mov_b64_e32 v[122:123], 0
	v_mov_b64_e32 v[124:125], 0
	v_mov_b64_e32 v[74:75], 0
	v_mov_b64_e32 v[76:77], 0
	v_mov_b64_e32 v[78:79], 0
	v_mov_b64_e32 v[80:81], 0
	v_mov_b64_e32 v[90:91], 0
	v_mov_b64_e32 v[92:93], 0
	v_mov_b64_e32 v[94:95], 0
	v_mov_b64_e32 v[96:97], 0
	v_mov_b64_e32 v[106:107], 0
	v_mov_b64_e32 v[108:109], 0
	v_mov_b64_e32 v[110:111], 0
	v_mov_b64_e32 v[112:113], 0
	v_mov_b64_e32 v[126:127], 0
	v_mov_b64_e32 v[128:129], 0
	v_mov_b64_e32 v[130:131], 0
	v_mov_b64_e32 v[132:133], 0

.LBB0_537:
	s_or_b64 exec, exec, s[10:11]
	s_andn2_b64 vcc, exec, s[70:71]
	s_cbranch_vccnz .LBB0_591
	s_cmpk_lt_u32 s55, 0x8080
	s_cbranch_scc1 .Lcpsq_n
	s_waitcnt vmcnt(0)
.Lcpsq_n:
	s_waitcnt vmcnt(8)
	global_store_dwordx4 v[248:249], v[114:117], off nt
	global_store_dwordx4 v[250:251], v[134:137], off nt
	global_store_dwordx4 v[252:253], v[138:141], off nt
	global_store_dwordx4 v[254:255], v[142:145], off nt
	s_branch .LBB0_591
